# w_up + w_gate-tail f32->bf16 conversion moved from the P0 prologue into the load segments of the P1 GEMM K-loop (1 32x32 item per 4 iterations per wave)
# speedup vs baseline: 1.0244x; 1.0244x over previous
; __global__ void __launch_bounds__(NWAVES * 64, 2) fwd(Args args) {
;     ...
;         if (embed) {
;             p0_transpose_matrix(w_gate + (size_t)(32 * CV_GATE_KB) * DFF, D - 32 * CV_GATE_KB, DFF, WguT + 32 * CV_GATE_KB, D, 1, scr, gw, NGW, F.lane, g_ffn + 32 * CV_GATE_KB);
;         } else {
;             p0_transpose_matrix(w_up_pool, PW, D, WupT, D, 0, scr, gw, NGW, F.lane);
;             p0_transpose_matrix(w_up_hgrn, HW, D, WupT + PW, D, 0, scr, gw, NGW, F.lane);
;             p0_transpose_matrix(w_out, D, D, WoT, D, 0, scr, gw, NGW, F.lane);
;             p0_transpose_matrix(w_gate, D, DFF, WguT, D, 1, scr, gw, NGW, F.lane, g_ffn);
;         }
;         p0_transpose_matrix(w_up, D, DFF, WguT, D, 2, scr, gw, NGW, F.lane, g_ffn);
.LBB0_50:
	s_branch .LBB0_73
	s_and_b64 vcc, exec, s[4:5]
	s_cbranch_vccz .LBB0_54
	s_cmpk_gt_i32 s80, 0x16d7
	s_cbranch_scc1 .LBB0_54
	v_mov_b32_e32 v13, 0
	v_lshl_add_u64 v[2:3], s[42:43], 0, v[12:13]
	s_mov_b64 s[4:5], 0x7e50000
	s_add_u32 s0, s40, 0x2f00
	v_lshl_add_u64 v[2:3], v[2:3], 0, s[4:5]
	v_lshl_add_u64 v[4:5], v[10:11], 1, s[68:69]
	s_mov_b64 s[4:5], 0xd301780
	s_addc_u32 s1, s41, 0
	v_lshl_add_u64 v[4:5], v[4:5], 0, s[4:5]
	s_lshl_b32 s4, s80, 5
	s_lshl_b32 s5, s80, 6
	s_lshl_b32 s6, s82, 6
	s_mov_b32 s7, 0xac00
	s_movk_i32 s9, 0x7fff
	s_mov_b32 s14, 0xffff0000
	s_mov_b32 s15, s80

; #define PG8_STAGE(bufoff, gbase, voff) do { _Pragma("unroll") for (int _i = 0; _i < 2; ++_i) \
;         __builtin_amdgcn_global_load_lds((const unsigned*)((const char*)(gbase) + (voff)[_i]), (PG8_LAS unsigned*)(lds + (bufoff) + ldsw + _i * 8192), 16, 0, 0); } while (0)
; #define PG8_WAIT_V(n) asm volatile("s_waitcnt vmcnt(" #n ")" ::: "memory")
; #define PG8_BAR __builtin_amdgcn_s_barrier()
; template <class Epi, class Sched, bool ALIGN_EPI = false, bool SP2 = false>
; __device__ __forceinline__ void gemm_phase(PG8_LAS unsigned char* lds, const Gemm g, const Sched& S, const Epi& E) {
;     ...
;         PG8_STAGE(PG8_SB(0, 0), cB, voffB); PG8_STAGE(PG8_SB(0, 1), cB + hstepB, voffB); PG8_STAGE(PG8_SA(0, 0), cA, voffA); PG8_STAGE(PG8_SA(0, 1), cA + hstepA, voffA);
;         if (wr == 1) PG8_BAR;
;         PG8_WAIT_V(2); PG8_BAR;
;         PG8_STAGE(PG8_SB(1, 0), cB + kstep, voffB); PG8_STAGE(PG8_SA(1, 0), cA + kstep, voffA); PG8_STAGE(PG8_SB(1, 1), cB + hstepB + kstep, voffB);
;         PG8_WAIT_V(6); PG8_BAR;
.LBB0_137:
	s_lshl_b32 s5, s5, 5
	s_mov_b64 s[18:19], 0x80
	s_and_b32 s5, s5, 0x60
	s_add_i32 m0, s55, 0x18000
	v_lshl_add_u64 v[8:9], v[8:9], 0, s[18:19]
	s_lshl_b32 s1, s4, 13
	s_lshl_b32 s22, s5, 7
	s_waitcnt vmcnt(2)
	s_barrier
	global_load_lds_dwordx4 v[8:9], off
	v_lshl_add_u64 v[4:5], v[4:5], 0, s[18:19]
	s_add_i32 m0, s55, 0x1a000
	s_add_i32 s75, s55, 0x8000
	s_add_i32 s76, s55, 0xa000
	global_load_lds_dwordx4 v[4:5], off
	v_lshl_add_u64 v[2:3], v[2:3], 0, s[18:19]
	s_mov_b32 m0, s75
	s_add_u32 s20, s8, 0x100080
	global_load_lds_dwordx4 v[2:3], off
	v_lshl_add_u64 v[2:3], v[6:7], 0, s[18:19]
	s_mov_b32 m0, s76
	s_addc_u32 s21, s9, 0
	global_load_lds_dwordx4 v[2:3], off
	s_add_i32 m0, s55, 0x1c000
	v_lshl_add_u64 v[2:3], s[20:21], 0, v[140:141]
	global_load_lds_dwordx4 v[2:3], off
	v_lshl_add_u64 v[2:3], s[20:21], 0, v[144:145]
	s_add_i32 m0, s55, 0x1e000
	v_and_b32_e32 v4, 32, v162
	global_load_lds_dwordx4 v[2:3], off
	v_and_b32_e32 v2, 15, v0
	v_lshlrev_b32_e32 v3, 1, v14
	v_lshl_or_b32 v163, s4, 6, v2
	v_lshl_or_b32 v2, v2, 6, v3
	v_bitop3_b32 v2, v2, s1, v4 bitop3:0xde
	v_lshlrev_b32_e32 v5, 6, v0
	s_movk_i32 s1, 0x3c0
	v_and_or_b32 v3, v5, s1, v3
	v_bitop3_b32 v164, s22, v3, v4 bitop3:0xf6
	v_lshlrev_b32_e32 v3, 10, v0
	v_and_b32_e32 v3, 0x60000, v3
	v_lshlrev_b32_e32 v4, 13, v12
	v_or3_b32 v3, v10, v3, v4
	s_cmpk_lt_u32 s14, 0x100
	v_add_u32_e32 v148, v3, v11
	v_lshlrev_b32_e32 v3, 6, v13
	s_waitcnt vmcnt(6)
	s_cselect_b64 s[20:21], -1, 0
	s_add_u32 s22, s62, 0x2000
	v_and_b32_e32 v3, 0xe0000, v3
	v_or_b32_e32 v165, s5, v14
	s_addc_u32 s23, s63, 0
	v_or3_b32 v3, v10, v3, v4
	s_add_i32 s83, 0, 0x10000
	s_add_i32 s89, 0, 0x14000
	v_or_b32_e32 v166, 0xffffec00, v165
	s_ashr_i32 s77, s74, 31
	s_ashr_i32 s81, s2, 31
	v_mov_b32_e32 v149, v147
	v_add_u32_e32 v150, v3, v11
	v_mov_b32_e32 v151, v147
	v_mov_b64_e32 v[152:153], 0x900
	v_mov_b64_e32 v[154:155], 0x8ff
	v_add_u32_e32 v167, s83, v164
	v_add_u32_e32 v168, s89, v164
	v_add_u32_e32 v169, 0, v2
	s_mov_b32 s90, 0xc2a00000
	s_mov_b32 s91, 0xc1f00000
	v_mov_b32_e32 v170, 0x42a00000
	v_mov_b32_e32 v171, 0x41f00000
	s_mov_b32 s92, 0
	s_barrier
	s_mov_b32 s32, 0
	s_mov_b32 s97, 0
	v_readlane_b32 s98, v244, 0
	v_readlane_b32 s99, v244, 1
	s_nop 3
	s_sub_u32 s98, s98, 0x98
	s_subb_u32 s99, s99, 0
	s_load_dwordx2 s[100:101], s[98:99], 0x58
	s_waitcnt lgkmcnt(0)
	v_writelane_b32 v245, s100, 0
	v_writelane_b32 v245, s101, 1
	s_nop 1
	s_load_dwordx2 s[100:101], s[98:99], 0x60
	s_waitcnt lgkmcnt(0)
	v_writelane_b32 v245, s100, 2
	v_writelane_b32 v245, s101, 3
	s_nop 1
	s_load_dwordx2 s[100:101], s[98:99], 0x50
	s_waitcnt lgkmcnt(0)
	v_writelane_b32 v245, s100, 4
	v_writelane_b32 v245, s101, 5
	s_mul_hi_u32 s93, s80, 0xbe82fa0c
	s_lshr_b32 s93, s93, 8
	s_mul_i32 s85, s93, 0x158
	s_sub_i32 s85, s80, s85
	s_lshl_b32 s93, s93, 16
	s_or_b32 s85, s85, s93
	s_mov_b64 s[100:101], 0
	s_branch .LBB0_140

; __device__ __forceinline__ unsigned cvt_pk_bf16(float lo, float hi) { const cvt_f2 v = {lo, hi}; return __builtin_bit_cast(unsigned, __builtin_convertvector(v, cvt_b2)); }
; #define GAS __attribute__((address_space(1)))
; #define LAS __attribute__((address_space(3)))
; #define LDS_WAIT() asm volatile("s_waitcnt lgkmcnt(0)" ::: "memory")
; __device__ __forceinline__ void conv_load(const ConvItem& it, int lane, f32x4 (&v)[4]) {
;     const int lk = lane >> 3, ln = (lane & 7) * 4;
; #pragma unroll
;     for (int i = 0; i < 4; ++i) v[i] = __builtin_nontemporal_load((const GAS f32x4*)(it.W + (size_t)(it.k0 + 8 * i + lk) * it.N + it.n0 + ln));
; }
; __device__ __forceinline__ void conv_store(const ConvItem& it, int lane, const f32x4 (&v)[4], LAS bf16* scr) {
;     const int lk = lane >> 3, ln = (lane & 7) * 4;
; #pragma unroll
;     for (int i = 0; i < 4; ++i) { const float gk = it.kgain ? it.kgain[it.k0 + 8 * i + lk] : 1.0f; LAS unsigned* p = (LAS unsigned*)(scr + (8 * i + lk) * 34 + ln); p[0] = pg8::cvt_pk_bf16(v[i][0] * gk, v[i][1] * gk); p[1] = pg8::cvt_pk_bf16(v[i][2] * gk, v[i][3] * gk); }
;     LDS_WAIT(); asm volatile("" ::: "memory");
;     const int c = lane & 3;
; #pragma unroll
;     for (int j = 0; j < 2; ++j) { const int n = (lane >> 2) + 16 * j; const LAS bf16* sp = scr + (8 * c) * 34 + n;
;         v4u o; o.x = (unsigned)sp[0] | ((unsigned)sp[34] << 16); o.y = (unsigned)sp[68] | ((unsigned)sp[102] << 16); o.z = (unsigned)sp[136] | ((unsigned)sp[170] << 16); o.w = (unsigned)sp[204] | ((unsigned)sp[238] << 16);
;         const int ng = it.n0 + n; const int row = it.rowmode == 0 ? ng : ((ng >> 7) * 256 + (it.rowmode == 2 ? 128 : 0) + (ng & 127));
;         __builtin_nontemporal_store(o, (GAS v4u*)(it.WT + (size_t)row * it.ldt + it.k0 + 8 * c)); }
;     LDS_WAIT(); asm volatile("" ::: "memory");
; }
.LBB0_143:
	s_and_b32 s93, s32, 3
	s_add_i32 s32, s32, 1
	s_mov_b32 s97, 0
	s_cmp_lg_u32 s93, 0
	s_cbranch_scc1 .Leng_not0
	s_lshr_b32 s93, s85, 16
	s_mov_b64 s[100:101], 0
	s_cmp_ge_u32 s93, 0xa2
	s_cbranch_scc1 .Leng_done
	s_cmp_lt_u32 s93, 0x80
	s_cbranch_scc0 .Leng_gate
	v_readlane_b32 s98, v245, 2
	v_readlane_b32 s99, v245, 3
	s_movk_i32 s100, 0x80
	s_branch .Leng_mat
.Leng_gate:
	v_readlane_b32 s98, v245, 0
	v_readlane_b32 s99, v245, 1
	s_sub_i32 s93, s93, 34
	s_mov_b32 s100, 0
.Leng_mat:
	v_lshrrev_b32_e32 v254, 3, v1
	v_mul_u32_u24_e32 v254, 0xac00, v254
	v_and_b32_e32 v255, 7, v1
	v_lshl_add_u32 v254, v255, 4, v254
	s_and_b32 s101, s85, 0xffff
	s_mul_i32 s97, s93, 0x158000
	s_add_u32 s98, s98, s97
	s_addc_u32 s99, s99, 0
	s_lshl_b32 s97, s101, 7
	s_add_u32 s98, s98, s97
	s_addc_u32 s99, s99, 0
	global_load_dwordx4 v[232:235], v254, s[98:99] nt
	s_add_u32 s98, s98, 0x56000
	s_addc_u32 s99, s99, 0
	global_load_dwordx4 v[236:239], v254, s[98:99] nt
	s_add_u32 s98, s98, 0x56000
	s_addc_u32 s99, s99, 0
	global_load_dwordx4 v[240:243], v254, s[98:99] nt
	s_add_u32 s98, s98, 0x56000
	s_addc_u32 s99, s99, 0
	global_load_dwordx4 v[246:249], v254, s[98:99] nt
	s_lshr_b32 s97, s101, 2
	s_lshl_b32 s97, s97, 8
	s_add_i32 s100, s100, s97
	s_and_b32 s97, s101, 3
	s_lshl_b32 s97, s97, 5
	s_add_i32 s100, s100, s97
	s_lshl_b32 s100, s100, 13
	s_lshl_b32 s97, s93, 6
	s_add_i32 s100, s100, s97
	v_readlane_b32 s98, v245, 4
	v_readlane_b32 s99, v245, 5
	v_readlane_b32 s97, v244, 6
	v_readlane_b32 s101, v244, 7
	v_lshrrev_b32_e32 v255, 3, v1
	v_lshlrev_b32_e32 v255, 2, v255
	s_lshl_b32 s93, s93, 7
	s_nop 1
	s_add_u32 s98, s98, s93
	s_addc_u32 s99, s99, 0
	s_add_u32 s100, s97, s100
	s_addc_u32 s101, s101, 0
	global_load_dword v250, v255, s[98:99]
	global_load_dword v251, v255, s[98:99] offset:32
	global_load_dword v252, v255, s[98:99] offset:64
	global_load_dword v253, v255, s[98:99] offset:96
	s_mov_b32 s97, 8
	s_branch .Leng_done
.Leng_not0:
	s_cmp_eq_u64 s[100:101], 0
	s_cbranch_scc1 .Leng_adv
	s_cmp_lg_u32 s93, 1
	s_cbranch_scc1 .Leng_not1
	v_readlane_b32 s93, v244, 10
	v_lshrrev_b32_e32 v254, 3, v1
	v_mul_u32_u24_e32 v254, 0x44, v254
	v_and_b32_e32 v255, 7, v1
	v_lshl_add_u32 v254, v255, 3, v254
	s_mulk_i32 s93, 0x900
	s_add_i32 s93, s93, 0x22400
	v_add_u32_e32 v254, s93, v254
	v_add_u32_e32 v255, 0x440, v254
	v_mul_f32_e32 v232, v250, v232
	v_mul_f32_e32 v233, v250, v233
	v_mul_f32_e32 v234, v250, v234
	v_mul_f32_e32 v235, v250, v235
	v_cvt_pk_bf16_f32 v232, v232, v233
	v_cvt_pk_bf16_f32 v233, v234, v235
	ds_write2_b32 v254, v232, v233 offset1:1
	v_mul_f32_e32 v236, v251, v236
	v_mul_f32_e32 v237, v251, v237
	v_mul_f32_e32 v238, v251, v238
	v_mul_f32_e32 v239, v251, v239
	v_cvt_pk_bf16_f32 v236, v236, v237
	v_cvt_pk_bf16_f32 v237, v238, v239
	ds_write2_b32 v254, v236, v237 offset0:136 offset1:137
	v_mul_f32_e32 v240, v252, v240
	v_mul_f32_e32 v241, v252, v241
	v_mul_f32_e32 v242, v252, v242
	v_mul_f32_e32 v243, v252, v243
	v_cvt_pk_bf16_f32 v240, v240, v241
	v_cvt_pk_bf16_f32 v241, v242, v243
	ds_write2_b32 v255, v240, v241 offset1:1
	v_mul_f32_e32 v246, v253, v246
	v_mul_f32_e32 v247, v253, v247
	v_mul_f32_e32 v248, v253, v248
	v_mul_f32_e32 v249, v253, v249
	v_cvt_pk_bf16_f32 v246, v246, v247
	v_cvt_pk_bf16_f32 v247, v248, v249
	ds_write2_b32 v255, v246, v247 offset0:136 offset1:137
	s_branch .Leng_done
.Leng_not1:
	s_cmp_lg_u32 s93, 2
	s_cbranch_scc1 .Leng_st3
	v_readlane_b32 s93, v244, 10
	v_and_b32_e32 v254, 3, v1
	v_mul_u32_u24_e32 v254, 0x220, v254
	v_lshrrev_b32_e32 v255, 2, v1
	v_lshl_add_u32 v254, v255, 1, v254
	s_mulk_i32 s93, 0x900
	s_add_i32 s93, s93, 0x22400
	v_add_u32_e32 v254, s93, v254
	ds_read_u16 v232, v254
	ds_read_u16 v233, v254 offset:68
	ds_read_u16 v234, v254 offset:136
	ds_read_u16 v235, v254 offset:204
	ds_read_u16 v236, v254 offset:272
	ds_read_u16 v237, v254 offset:340
	ds_read_u16 v238, v254 offset:408
	ds_read_u16 v239, v254 offset:476
	ds_read_u16 v240, v254 offset:32
	ds_read_u16 v241, v254 offset:100
	ds_read_u16 v242, v254 offset:168
	ds_read_u16 v243, v254 offset:236
	ds_read_u16 v246, v254 offset:304
	ds_read_u16 v247, v254 offset:372
	ds_read_u16 v248, v254 offset:440
	ds_read_u16 v249, v254 offset:508
	s_branch .Leng_done
.Leng_st3:
	v_and_b32_e32 v254, 3, v1
	v_lshlrev_b32_e32 v254, 4, v254
	v_lshrrev_b32_e32 v255, 2, v1
	v_lshl_add_u32 v254, v255, 13, v254
	v_add_u32_e32 v255, 0x20000, v254
	v_lshl_or_b32 v232, v233, 16, v232
	v_lshl_or_b32 v233, v235, 16, v234
	v_lshl_or_b32 v234, v237, 16, v236
	v_lshl_or_b32 v235, v239, 16, v238
	v_lshl_or_b32 v236, v241, 16, v240
	v_lshl_or_b32 v237, v243, 16, v242
	v_lshl_or_b32 v238, v247, 16, v246
	v_lshl_or_b32 v239, v249, 16, v248
	global_store_dwordx4 v254, v[232:235], s[100:101] nt
	global_store_dwordx4 v255, v[236:239], s[100:101] nt
	s_mov_b32 s97, 2
.Leng_adv:
	s_cmp_lg_u32 s93, 3
	s_cbranch_scc1 .Leng_done
	s_add_i32 s85, s85, 0x50148
	s_and_b32 s93, s85, 0xffff
	s_cmp_ge_u32 s93, 0x158
	s_cbranch_scc0 .Leng_done
	s_add_i32 s85, s85, 0xfea8
; #define PG8_STAGE(bufoff, gbase, voff) do { _Pragma("unroll") for (int _i = 0; _i < 2; ++_i) \
;         __builtin_amdgcn_global_load_lds((const unsigned*)((const char*)(gbase) + (voff)[_i]), (PG8_LAS unsigned*)(lds + (bufoff) + ldsw + _i * 8192), 16, 0, 0); } while (0)
; #define PG8_LDA(dst, b, h) do { _Pragma("unroll") for (int m = 0; m < 4; ++m) _Pragma("unroll") for (int k = 0; k < 2; ++k) dst[m][k] = *(const PG8_LAS bf16x8*)(lds + PG8_SA(b, h) + aoff + m * 2048 + k * 1024); } while (0)
; #define PG8_LDB(dst, b, h) do { _Pragma("unroll") for (int n = 0; n < 2; ++n) _Pragma("unroll") for (int k = 0; k < 2; ++k) dst[n][k] = *(const PG8_LAS bf16x8*)(lds + PG8_SB(b, h) + boff + n * 2048 + k * 1024); } while (0)
; #define PG8_MMA(ai, bj, At, Bt) do { __builtin_amdgcn_s_setprio(3); _Pragma("unroll") for (int m = 0; m < 4; ++m) _Pragma("unroll") for (int n = 0; n < 2; ++n) _Pragma("unroll") for (int k = 0; k < 2; ++k) \
;         acc[ai][bj][m][n] = __builtin_amdgcn_mfma_f32_16x16x32_bf16(Bt[n][k], At[m][k], acc[ai][bj][m][n], 0, 0, 0); __builtin_amdgcn_s_setprio(0); } while (0)
; #define PG8_WAIT_V(n) asm volatile("s_waitcnt vmcnt(" #n ")" ::: "memory")
; #define PG8_WAIT_L(n) asm volatile("s_waitcnt lgkmcnt(" #n ")" ::: "memory")
; #define PG8_BAR __builtin_amdgcn_s_barrier()
; #define PG8_SCHED __builtin_amdgcn_sched_barrier(0)
; template <class Epi, class Sched, bool ALIGN_EPI = false, bool SP2 = false>
; __device__ __forceinline__ void gemm_phase(PG8_LAS unsigned char* lds, const Gemm g, const Sched& S, const Epi& E) {
;     ...
;             PG8_LDB(B0, 0, 0); PG8_LDB(B1, 0, 1); PG8_SCHED; PG8_LDA(At, 0, 0); PG8_STAGE(PG8_SA(1, 1), a1 + hstepA, voffA);
;             PG8_WAIT_V(8); PG8_WAIT_L(0); PG8_BAR; PG8_MMA(0, 0, At, B0); PG8_MMA(0, 1, At, B1); PG8_BAR; PG8_SCHED;
;             PG8_LDA(At, 0, 1); PG8_STAGE(PG8_SB(0, 0), b2, voffB); PG8_STAGE(PG8_SB(0, 1), b2 + hstepB, voffB); PG8_STAGE(PG8_SA(0, 0), a2, voffA);
;             PG8_WAIT_V(8); PG8_WAIT_L(0); PG8_BAR; PG8_MMA(1, 0, At, B0); PG8_MMA(1, 1, At, B1); PG8_BAR; PG8_SCHED;
.Leng_done:
	ds_read_b128 v[130:133], v167
	ds_read_b128 v[134:137], v167 offset:1024
	ds_read_b128 v[156:159], v167 offset:2048
	ds_read_b128 v[172:175], v167 offset:3072
	ds_read_b128 v[176:179], v168
	ds_read_b128 v[180:183], v168 offset:1024
	ds_read_b128 v[184:187], v168 offset:2048
	ds_read_b128 v[188:191], v168 offset:3072
	s_add_u32 s8, s6, 0xfff00080
	s_addc_u32 s9, s7, -1
	s_cmp_eq_u32 s45, 60
	s_cselect_b32 s37, s1, s9
	s_cselect_b32 s36, s14, s8
	s_cselect_b32 s9, s25, s44
	s_cselect_b32 s8, s27, s33
	v_lshl_add_u64 v[160:161], s[6:7], 0, v[148:149]
	s_add_i32 m0, s55, 0xc000
	ds_read_b128 v[192:195], v169
	ds_read_b128 v[196:199], v169 offset:1024
	ds_read_b128 v[200:203], v169 offset:2048
	ds_read_b128 v[204:207], v169 offset:3072
	ds_read_b128 v[208:211], v169 offset:4096
	ds_read_b128 v[212:215], v169 offset:5120
	ds_read_b128 v[216:219], v169 offset:6144
	ds_read_b128 v[220:223], v169 offset:7168
	global_load_lds_dwordx4 v[160:161], off
	v_lshl_add_u64 v[160:161], s[6:7], 0, v[150:151]
	s_add_i32 m0, s55, 0xe000
	s_nop 0
	global_load_lds_dwordx4 v[160:161], off
	s_cmp_eq_u32 s97, 0
	s_cbranch_scc1 .Lengw1_a
	s_cmp_eq_u32 s97, 2
	s_cbranch_scc1 .Lengw1_b
	s_waitcnt vmcnt(16)
	s_branch .Lengw1_e
.Lengw1_b:
	s_waitcnt vmcnt(10)
	s_branch .Lengw1_e
.Lengw1_a:
	s_waitcnt vmcnt(8)
.Lengw1_e:
	s_waitcnt lgkmcnt(0)
	s_barrier
	s_setprio 3
	s_waitcnt lgkmcnt(0)
	v_mfma_f32_16x16x32_bf16 v[126:129], v[130:133], v[192:195], v[126:129]
	v_mfma_f32_16x16x32_bf16 v[118:121], v[156:159], v[192:195], v[118:121]
	v_mfma_f32_16x16x32_bf16 v[110:113], v[130:133], v[200:203], v[110:113]
	v_mfma_f32_16x16x32_bf16 v[102:105], v[156:159], v[200:203], v[102:105]
	v_mfma_f32_16x16x32_bf16 v[94:97], v[130:133], v[208:211], v[94:97]
	v_mfma_f32_16x16x32_bf16 v[86:89], v[156:159], v[208:211], v[86:89]
	v_mfma_f32_16x16x32_bf16 v[78:81], v[130:133], v[216:219], v[78:81]
	v_mfma_f32_16x16x32_bf16 v[70:73], v[156:159], v[216:219], v[70:73]
	v_mfma_f32_16x16x32_bf16 v[126:129], v[134:137], v[196:199], v[126:129]
	v_mfma_f32_16x16x32_bf16 v[118:121], v[172:175], v[196:199], v[118:121]
	v_mfma_f32_16x16x32_bf16 v[110:113], v[134:137], v[204:207], v[110:113]
	v_mfma_f32_16x16x32_bf16 v[102:105], v[172:175], v[204:207], v[102:105]
	v_mfma_f32_16x16x32_bf16 v[94:97], v[134:137], v[212:215], v[94:97]
	v_mfma_f32_16x16x32_bf16 v[86:89], v[172:175], v[212:215], v[86:89]
	v_mfma_f32_16x16x32_bf16 v[78:81], v[134:137], v[220:223], v[78:81]
	v_mfma_f32_16x16x32_bf16 v[70:73], v[172:175], v[220:223], v[70:73]
	s_setprio 0
	s_setprio 3
	v_mfma_f32_16x16x32_bf16 v[122:125], v[176:179], v[192:195], v[122:125]
	v_mfma_f32_16x16x32_bf16 v[114:117], v[184:187], v[192:195], v[114:117]
	v_mfma_f32_16x16x32_bf16 v[106:109], v[176:179], v[200:203], v[106:109]
	v_mfma_f32_16x16x32_bf16 v[98:101], v[184:187], v[200:203], v[98:101]
	v_mfma_f32_16x16x32_bf16 v[90:93], v[176:179], v[208:211], v[90:93]
	v_mfma_f32_16x16x32_bf16 v[82:85], v[184:187], v[208:211], v[82:85]
	v_mfma_f32_16x16x32_bf16 v[74:77], v[176:179], v[216:219], v[74:77]
	v_mfma_f32_16x16x32_bf16 v[66:69], v[184:187], v[216:219], v[66:69]
	v_mfma_f32_16x16x32_bf16 v[122:125], v[180:183], v[196:199], v[122:125]
	v_mfma_f32_16x16x32_bf16 v[114:117], v[188:191], v[196:199], v[114:117]
	v_mfma_f32_16x16x32_bf16 v[106:109], v[180:183], v[204:207], v[106:109]
	v_mfma_f32_16x16x32_bf16 v[98:101], v[188:191], v[204:207], v[98:101]
	v_mfma_f32_16x16x32_bf16 v[90:93], v[180:183], v[212:215], v[90:93]
	v_mfma_f32_16x16x32_bf16 v[82:85], v[188:191], v[212:215], v[82:85]
	v_mfma_f32_16x16x32_bf16 v[74:77], v[180:183], v[220:223], v[74:77]
	v_mfma_f32_16x16x32_bf16 v[66:69], v[188:191], v[220:223], v[66:69]
	s_setprio 0
	s_barrier
	s_add_i32 s56, s83, s66
	v_lshl_add_u64 v[160:161], s[8:9], 0, v[140:141]
	s_mov_b32 m0, s56
	ds_read_b128 v[192:195], v169 offset:16384
	ds_read_b128 v[196:199], v169 offset:17408
	ds_read_b128 v[200:203], v169 offset:18432
	ds_read_b128 v[204:207], v169 offset:19456
	ds_read_b128 v[208:211], v169 offset:20480
	ds_read_b128 v[212:215], v169 offset:21504
	ds_read_b128 v[216:219], v169 offset:22528
	ds_read_b128 v[220:223], v169 offset:23552
	global_load_lds_dwordx4 v[160:161], off
	s_add_i32 m0, s56, 0x2000
	s_add_u32 s56, s8, 0x100000
	v_lshl_add_u64 v[224:225], s[8:9], 0, v[144:145]
	s_addc_u32 s57, s9, 0
	s_add_i32 s58, s89, s66
	global_load_lds_dwordx4 v[224:225], off
	v_lshl_add_u64 v[226:227], s[56:57], 0, v[140:141]
	s_mov_b32 m0, s58
	v_lshl_add_u64 v[228:229], s[36:37], 0, v[142:143]
	global_load_lds_dwordx4 v[226:227], off
	v_lshl_add_u64 v[226:227], s[56:57], 0, v[144:145]
	s_add_i32 m0, s58, 0x2000
	s_nop 0
	global_load_lds_dwordx4 v[226:227], off
	v_lshl_add_u64 v[226:227], s[36:37], 0, v[138:139]
	s_mov_b32 m0, s55
	s_nop 0
	global_load_lds_dwordx4 v[226:227], off
	s_mov_b32 m0, s67
	s_nop 0
	global_load_lds_dwordx4 v[228:229], off
	s_cmp_eq_u32 s97, 0
	s_cbranch_scc1 .Lengw2_a
	s_cmp_eq_u32 s97, 2
	s_cbranch_scc1 .Lengw2_b
	s_waitcnt vmcnt(16)
	s_branch .Lengw2_e

; #define PG8_STAGE(bufoff, gbase, voff) do { _Pragma("unroll") for (int _i = 0; _i < 2; ++_i) \
;         __builtin_amdgcn_global_load_lds((const unsigned*)((const char*)(gbase) + (voff)[_i]), (PG8_LAS unsigned*)(lds + (bufoff) + ldsw + _i * 8192), 16, 0, 0); } while (0)
; #define PG8_LDA(dst, b, h) do { _Pragma("unroll") for (int m = 0; m < 4; ++m) _Pragma("unroll") for (int k = 0; k < 2; ++k) dst[m][k] = *(const PG8_LAS bf16x8*)(lds + PG8_SA(b, h) + aoff + m * 2048 + k * 1024); } while (0)
; #define PG8_LDB(dst, b, h) do { _Pragma("unroll") for (int n = 0; n < 2; ++n) _Pragma("unroll") for (int k = 0; k < 2; ++k) dst[n][k] = *(const PG8_LAS bf16x8*)(lds + PG8_SB(b, h) + boff + n * 2048 + k * 1024); } while (0)
; #define PG8_MMA(ai, bj, At, Bt) do { __builtin_amdgcn_s_setprio(3); _Pragma("unroll") for (int m = 0; m < 4; ++m) _Pragma("unroll") for (int n = 0; n < 2; ++n) _Pragma("unroll") for (int k = 0; k < 2; ++k) \
;         acc[ai][bj][m][n] = __builtin_amdgcn_mfma_f32_16x16x32_bf16(Bt[n][k], At[m][k], acc[ai][bj][m][n], 0, 0, 0); __builtin_amdgcn_s_setprio(0); } while (0)
; #define PG8_WAIT_V(n) asm volatile("s_waitcnt vmcnt(" #n ")" ::: "memory")
; #define PG8_WAIT_L(n) asm volatile("s_waitcnt lgkmcnt(" #n ")" ::: "memory")
; #define PG8_BAR __builtin_amdgcn_s_barrier()
; #define PG8_SCHED __builtin_amdgcn_sched_barrier(0)
; template <class Epi, class Sched, bool ALIGN_EPI = false, bool SP2 = false>
; __device__ __forceinline__ void gemm_phase(PG8_LAS unsigned char* lds, const Gemm g, const Sched& S, const Epi& E) {
;     ...
;             PG8_WAIT_V(8); PG8_WAIT_L(0); PG8_BAR; PG8_MMA(1, 0, At, B0); PG8_MMA(1, 1, At, B1); PG8_BAR; PG8_SCHED;
;             PG8_LDB(B0, 1, 0); PG8_LDB(B1, 1, 1); PG8_SCHED; PG8_LDA(At, 1, 0); PG8_STAGE(PG8_SA(0, 1), a2 + hstepA, voffA);
;             PG8_WAIT_V(8); PG8_WAIT_L(0); PG8_BAR; PG8_MMA(0, 0, At, B0); PG8_MMA(0, 1, At, B1); PG8_BAR; PG8_SCHED;
.Lengw2_e:
	s_waitcnt lgkmcnt(0)
	s_barrier
	s_setprio 3
	s_waitcnt lgkmcnt(0)
	v_mfma_f32_16x16x32_bf16 v[62:65], v[130:133], v[192:195], v[62:65]
	v_mfma_f32_16x16x32_bf16 v[54:57], v[156:159], v[192:195], v[54:57]
	v_mfma_f32_16x16x32_bf16 v[46:49], v[130:133], v[200:203], v[46:49]
	v_mfma_f32_16x16x32_bf16 v[38:41], v[156:159], v[200:203], v[38:41]
	v_mfma_f32_16x16x32_bf16 v[30:33], v[130:133], v[208:211], v[30:33]
	v_mfma_f32_16x16x32_bf16 v[22:25], v[156:159], v[208:211], v[22:25]
	v_mfma_f32_16x16x32_bf16 v[14:17], v[130:133], v[216:219], v[14:17]
	v_mfma_f32_16x16x32_bf16 v[6:9], v[156:159], v[216:219], v[6:9]
	v_mfma_f32_16x16x32_bf16 v[62:65], v[134:137], v[196:199], v[62:65]
	v_mfma_f32_16x16x32_bf16 v[54:57], v[172:175], v[196:199], v[54:57]
	v_mfma_f32_16x16x32_bf16 v[46:49], v[134:137], v[204:207], v[46:49]
	v_mfma_f32_16x16x32_bf16 v[38:41], v[172:175], v[204:207], v[38:41]
	v_mfma_f32_16x16x32_bf16 v[30:33], v[134:137], v[212:215], v[30:33]
	v_mfma_f32_16x16x32_bf16 v[22:25], v[172:175], v[212:215], v[22:25]
	v_mfma_f32_16x16x32_bf16 v[14:17], v[134:137], v[220:223], v[14:17]
	v_mfma_f32_16x16x32_bf16 v[6:9], v[172:175], v[220:223], v[6:9]
	s_setprio 0
	s_setprio 3
	v_mfma_f32_16x16x32_bf16 v[58:61], v[176:179], v[192:195], v[58:61]
	v_mfma_f32_16x16x32_bf16 v[50:53], v[184:187], v[192:195], v[50:53]
	v_mfma_f32_16x16x32_bf16 v[42:45], v[176:179], v[200:203], v[42:45]
	v_mfma_f32_16x16x32_bf16 v[34:37], v[184:187], v[200:203], v[34:37]
	v_mfma_f32_16x16x32_bf16 v[26:29], v[176:179], v[208:211], v[26:29]
	v_mfma_f32_16x16x32_bf16 v[18:21], v[184:187], v[208:211], v[18:21]
	v_mfma_f32_16x16x32_bf16 v[10:13], v[176:179], v[216:219], v[10:13]
	v_mfma_f32_16x16x32_bf16 v[2:5], v[184:187], v[216:219], v[2:5]
	v_mfma_f32_16x16x32_bf16 v[58:61], v[180:183], v[196:199], v[58:61]
	v_mfma_f32_16x16x32_bf16 v[50:53], v[188:191], v[196:199], v[50:53]
	v_mfma_f32_16x16x32_bf16 v[42:45], v[180:183], v[204:207], v[42:45]
	v_mfma_f32_16x16x32_bf16 v[34:37], v[188:191], v[204:207], v[34:37]
	v_mfma_f32_16x16x32_bf16 v[26:29], v[180:183], v[212:215], v[26:29]
	v_mfma_f32_16x16x32_bf16 v[18:21], v[188:191], v[212:215], v[18:21]
	v_mfma_f32_16x16x32_bf16 v[10:13], v[180:183], v[220:223], v[10:13]
	v_mfma_f32_16x16x32_bf16 v[2:5], v[188:191], v[220:223], v[2:5]
	s_setprio 0
	s_barrier
	s_add_i32 s56, 0, 0x18000
	v_add_u32_e32 v146, s56, v164
	s_add_i32 s57, 0, 0x1c000
	ds_read_b128 v[130:133], v146
	ds_read_b128 v[134:137], v146 offset:1024
	ds_read_b128 v[156:159], v146 offset:2048
	ds_read_b128 v[172:175], v146 offset:3072
	v_add_u32_e32 v146, s57, v164
	ds_read_b128 v[176:179], v146
	ds_read_b128 v[180:183], v146 offset:1024
	ds_read_b128 v[184:187], v146 offset:2048
	ds_read_b128 v[188:191], v146 offset:3072
	s_add_u32 s36, s36, 0x100000
	s_addc_u32 s37, s37, 0
	s_mov_b32 m0, s72
	v_lshl_add_u64 v[230:231], s[36:37], 0, v[138:139]
	ds_read_b128 v[192:195], v169 offset:32768
	ds_read_b128 v[196:199], v169 offset:33792
	ds_read_b128 v[200:203], v169 offset:34816
	ds_read_b128 v[204:207], v169 offset:35840
	ds_read_b128 v[208:211], v169 offset:36864
	ds_read_b128 v[212:215], v169 offset:37888
	ds_read_b128 v[216:219], v169 offset:38912
	ds_read_b128 v[220:223], v169 offset:39936
	global_load_lds_dwordx4 v[230:231], off
	v_lshl_add_u64 v[230:231], s[36:37], 0, v[142:143]
	s_mov_b32 m0, s73
	s_nop 0
	global_load_lds_dwordx4 v[230:231], off
	s_waitcnt vmcnt(8)
	s_waitcnt lgkmcnt(0)
	s_barrier
	s_setprio 3
	s_waitcnt lgkmcnt(0)
	v_mfma_f32_16x16x32_bf16 v[126:129], v[130:133], v[192:195], v[126:129]
	v_mfma_f32_16x16x32_bf16 v[118:121], v[156:159], v[192:195], v[118:121]
	v_mfma_f32_16x16x32_bf16 v[110:113], v[130:133], v[200:203], v[110:113]
	v_mfma_f32_16x16x32_bf16 v[102:105], v[156:159], v[200:203], v[102:105]
	v_mfma_f32_16x16x32_bf16 v[94:97], v[130:133], v[208:211], v[94:97]
	v_mfma_f32_16x16x32_bf16 v[86:89], v[156:159], v[208:211], v[86:89]
	v_mfma_f32_16x16x32_bf16 v[78:81], v[130:133], v[216:219], v[78:81]
	v_mfma_f32_16x16x32_bf16 v[70:73], v[156:159], v[216:219], v[70:73]
	v_mfma_f32_16x16x32_bf16 v[126:129], v[134:137], v[196:199], v[126:129]
	v_mfma_f32_16x16x32_bf16 v[118:121], v[172:175], v[196:199], v[118:121]
	v_mfma_f32_16x16x32_bf16 v[110:113], v[134:137], v[204:207], v[110:113]
	v_mfma_f32_16x16x32_bf16 v[102:105], v[172:175], v[204:207], v[102:105]
	v_mfma_f32_16x16x32_bf16 v[94:97], v[134:137], v[212:215], v[94:97]
	v_mfma_f32_16x16x32_bf16 v[86:89], v[172:175], v[212:215], v[86:89]
	v_mfma_f32_16x16x32_bf16 v[78:81], v[134:137], v[220:223], v[78:81]
	v_mfma_f32_16x16x32_bf16 v[70:73], v[172:175], v[220:223], v[70:73]
	s_setprio 0
	s_setprio 3
	v_mfma_f32_16x16x32_bf16 v[122:125], v[176:179], v[192:195], v[122:125]
	v_mfma_f32_16x16x32_bf16 v[114:117], v[184:187], v[192:195], v[114:117]
	v_mfma_f32_16x16x32_bf16 v[106:109], v[176:179], v[200:203], v[106:109]
	v_mfma_f32_16x16x32_bf16 v[98:101], v[184:187], v[200:203], v[98:101]
	v_mfma_f32_16x16x32_bf16 v[90:93], v[176:179], v[208:211], v[90:93]
	v_mfma_f32_16x16x32_bf16 v[82:85], v[184:187], v[208:211], v[82:85]
	v_mfma_f32_16x16x32_bf16 v[74:77], v[176:179], v[216:219], v[74:77]
	v_mfma_f32_16x16x32_bf16 v[66:69], v[184:187], v[216:219], v[66:69]
	v_mfma_f32_16x16x32_bf16 v[122:125], v[180:183], v[196:199], v[122:125]
	v_mfma_f32_16x16x32_bf16 v[114:117], v[188:191], v[196:199], v[114:117]
	v_mfma_f32_16x16x32_bf16 v[106:109], v[180:183], v[204:207], v[106:109]
	v_mfma_f32_16x16x32_bf16 v[98:101], v[188:191], v[204:207], v[98:101]
	v_mfma_f32_16x16x32_bf16 v[90:93], v[180:183], v[212:215], v[90:93]
	v_mfma_f32_16x16x32_bf16 v[82:85], v[188:191], v[212:215], v[82:85]
	v_mfma_f32_16x16x32_bf16 v[74:77], v[180:183], v[220:223], v[74:77]
	v_mfma_f32_16x16x32_bf16 v[66:69], v[188:191], v[220:223], v[66:69]
	s_setprio 0
	s_barrier
; #define PG8_STAGE(bufoff, gbase, voff) do { _Pragma("unroll") for (int _i = 0; _i < 2; ++_i) \
;         __builtin_amdgcn_global_load_lds((const unsigned*)((const char*)(gbase) + (voff)[_i]), (PG8_LAS unsigned*)(lds + (bufoff) + ldsw + _i * 8192), 16, 0, 0); } while (0)
; #define PG8_LDA(dst, b, h) do { _Pragma("unroll") for (int m = 0; m < 4; ++m) _Pragma("unroll") for (int k = 0; k < 2; ++k) dst[m][k] = *(const PG8_LAS bf16x8*)(lds + PG8_SA(b, h) + aoff + m * 2048 + k * 1024); } while (0)
; #define PG8_MMA(ai, bj, At, Bt) do { __builtin_amdgcn_s_setprio(3); _Pragma("unroll") for (int m = 0; m < 4; ++m) _Pragma("unroll") for (int n = 0; n < 2; ++n) _Pragma("unroll") for (int k = 0; k < 2; ++k) \
;         acc[ai][bj][m][n] = __builtin_amdgcn_mfma_f32_16x16x32_bf16(Bt[n][k], At[m][k], acc[ai][bj][m][n], 0, 0, 0); __builtin_amdgcn_s_setprio(0); } while (0)
; #define PG8_WAIT_V(n) asm volatile("s_waitcnt vmcnt(" #n ")" ::: "memory")
; #define PG8_WAIT_L(n) asm volatile("s_waitcnt lgkmcnt(" #n ")" ::: "memory")
; #define PG8_BAR __builtin_amdgcn_s_barrier()
; #define PG8_SCHED __builtin_amdgcn_sched_barrier(0)
; template <class Epi, class Sched, bool ALIGN_EPI = false, bool SP2 = false>
; __device__ __forceinline__ void gemm_phase(PG8_LAS unsigned char* lds, const Gemm g, const Sched& S, const Epi& E) {
;     ...
;             PG8_LDA(At, 1, 1); PG8_STAGE(PG8_SB(1, 0), b3, voffB); PG8_STAGE(PG8_SB(1, 1), b3 + hstepB, voffB); PG8_STAGE(PG8_SA(1, 0), a3, voffA);
;             PG8_WAIT_V(8); PG8_WAIT_L(0); PG8_BAR; PG8_MMA(1, 0, At, B0); PG8_MMA(1, 1, At, B1); PG8_BAR; PG8_SCHED;
	s_add_i32 s36, s56, s66
	v_lshl_add_u64 v[160:161], v[160:161], 0, s[18:19]
	s_mov_b32 m0, s36
	ds_read_b128 v[192:195], v169 offset:49152
	ds_read_b128 v[196:199], v169 offset:50176
	ds_read_b128 v[200:203], v169 offset:51200
	ds_read_b128 v[204:207], v169 offset:52224
	ds_read_b128 v[208:211], v169 offset:53248
	ds_read_b128 v[212:215], v169 offset:54272
	ds_read_b128 v[216:219], v169 offset:55296
	ds_read_b128 v[220:223], v169 offset:56320
	global_load_lds_dwordx4 v[160:161], off
	s_add_i32 m0, s36, 0x2000
	s_add_u32 s8, s8, 0x100080
	v_lshl_add_u64 v[160:161], v[224:225], 0, s[18:19]
	s_addc_u32 s9, s9, 0
	s_add_i32 s36, s57, s66
	global_load_lds_dwordx4 v[160:161], off
	v_lshl_add_u64 v[160:161], s[8:9], 0, v[140:141]
	s_mov_b32 m0, s36
	s_nop 0
	global_load_lds_dwordx4 v[160:161], off
	v_lshl_add_u64 v[160:161], s[8:9], 0, v[144:145]
	s_add_i32 m0, s36, 0x2000
	s_nop 0
	global_load_lds_dwordx4 v[160:161], off
	v_lshl_add_u64 v[160:161], v[226:227], 0, s[18:19]
	s_mov_b32 m0, s75
	s_nop 0
	global_load_lds_dwordx4 v[160:161], off
	v_lshl_add_u64 v[160:161], v[228:229], 0, s[18:19]
	s_mov_b32 m0, s76
	s_nop 0
	global_load_lds_dwordx4 v[160:161], off
	s_waitcnt vmcnt(8)
	s_waitcnt lgkmcnt(0)
	s_barrier
	s_setprio 3
	s_waitcnt lgkmcnt(0)
	v_mfma_f32_16x16x32_bf16 v[62:65], v[130:133], v[192:195], v[62:65]
	v_mfma_f32_16x16x32_bf16 v[54:57], v[156:159], v[192:195], v[54:57]
	v_mfma_f32_16x16x32_bf16 v[46:49], v[130:133], v[200:203], v[46:49]
	v_mfma_f32_16x16x32_bf16 v[38:41], v[156:159], v[200:203], v[38:41]
	v_mfma_f32_16x16x32_bf16 v[30:33], v[130:133], v[208:211], v[30:33]
	v_mfma_f32_16x16x32_bf16 v[22:25], v[156:159], v[208:211], v[22:25]
	v_mfma_f32_16x16x32_bf16 v[14:17], v[130:133], v[216:219], v[14:17]
	v_mfma_f32_16x16x32_bf16 v[6:9], v[156:159], v[216:219], v[6:9]
	v_mfma_f32_16x16x32_bf16 v[62:65], v[134:137], v[196:199], v[62:65]
	v_mfma_f32_16x16x32_bf16 v[54:57], v[172:175], v[196:199], v[54:57]
	v_mfma_f32_16x16x32_bf16 v[46:49], v[134:137], v[204:207], v[46:49]
	v_mfma_f32_16x16x32_bf16 v[38:41], v[172:175], v[204:207], v[38:41]
	v_mfma_f32_16x16x32_bf16 v[30:33], v[134:137], v[212:215], v[30:33]
	v_mfma_f32_16x16x32_bf16 v[22:25], v[172:175], v[212:215], v[22:25]
	v_mfma_f32_16x16x32_bf16 v[14:17], v[134:137], v[220:223], v[14:17]
	v_mfma_f32_16x16x32_bf16 v[6:9], v[172:175], v[220:223], v[6:9]
	s_setprio 0
	s_setprio 3
	v_mfma_f32_16x16x32_bf16 v[58:61], v[176:179], v[192:195], v[58:61]
	v_mfma_f32_16x16x32_bf16 v[50:53], v[184:187], v[192:195], v[50:53]
	v_mfma_f32_16x16x32_bf16 v[42:45], v[176:179], v[200:203], v[42:45]
	v_mfma_f32_16x16x32_bf16 v[34:37], v[184:187], v[200:203], v[34:37]
	v_mfma_f32_16x16x32_bf16 v[26:29], v[176:179], v[208:211], v[26:29]
	v_mfma_f32_16x16x32_bf16 v[18:21], v[184:187], v[208:211], v[18:21]
	v_mfma_f32_16x16x32_bf16 v[10:13], v[176:179], v[216:219], v[10:13]
	v_mfma_f32_16x16x32_bf16 v[2:5], v[184:187], v[216:219], v[2:5]
	v_mfma_f32_16x16x32_bf16 v[58:61], v[180:183], v[196:199], v[58:61]
	v_mfma_f32_16x16x32_bf16 v[50:53], v[188:191], v[196:199], v[50:53]
	v_mfma_f32_16x16x32_bf16 v[42:45], v[180:183], v[204:207], v[42:45]
	v_mfma_f32_16x16x32_bf16 v[34:37], v[188:191], v[204:207], v[34:37]
	v_mfma_f32_16x16x32_bf16 v[26:29], v[180:183], v[212:215], v[26:29]
	v_mfma_f32_16x16x32_bf16 v[18:21], v[188:191], v[212:215], v[18:21]
	v_mfma_f32_16x16x32_bf16 v[10:13], v[180:183], v[220:223], v[10:13]
	v_mfma_f32_16x16x32_bf16 v[2:5], v[188:191], v[220:223], v[2:5]
	s_setprio 0
	s_barrier
	s_add_i32 s45, s45, 2
	s_add_u32 s6, s6, 0x100
	s_addc_u32 s7, s7, 0
	s_add_u32 s33, s33, 0x100
	s_addc_u32 s44, s44, 0
	s_cmp_gt_u32 s45, 61
	s_cbranch_scc0 .LBB0_143
	s_and_b64 vcc, exec, s[20:21]
	s_cbranch_vccz .LBB0_148
	s_barrier
	v_lshl_add_u32 v156, s0, 8, v163
	s_cmp_lt_i32 s54, 40
	s_mov_b64 s[0:1], -1
	s_cbranch_scc1 .LBB0_149

; __global__ void __launch_bounds__(NWAVES * 64, 2) fwd(Args args) {
	.amdhsa_kernel _Z3fwd4Args
		.amdhsa_group_segment_fixed_size 0
		.amdhsa_private_segment_fixed_size 0
		.amdhsa_kernarg_size 408
		.amdhsa_user_sgpr_count 2
		.amdhsa_user_sgpr_dispatch_ptr 0
		.amdhsa_user_sgpr_queue_ptr 0
		.amdhsa_user_sgpr_kernarg_segment_ptr 1
		.amdhsa_user_sgpr_dispatch_id 0
		.amdhsa_user_sgpr_kernarg_preload_length 0
		.amdhsa_user_sgpr_kernarg_preload_offset 0
		.amdhsa_user_sgpr_private_segment_size 0
		.amdhsa_uses_dynamic_stack 0
		.amdhsa_enable_private_segment 0
		.amdhsa_system_sgpr_workgroup_id_x 1
		.amdhsa_system_sgpr_workgroup_id_y 0
		.amdhsa_system_sgpr_workgroup_id_z 0
		.amdhsa_system_sgpr_workgroup_info 0
		.amdhsa_system_vgpr_workitem_id 0
		.amdhsa_next_free_vgpr 256
		.amdhsa_next_free_sgpr 102
		.amdhsa_accum_offset 256
		.amdhsa_reserve_vcc 1
		.amdhsa_float_round_mode_32 0
		.amdhsa_float_round_mode_16_64 0
		.amdhsa_float_denorm_mode_32 3
		.amdhsa_float_denorm_mode_16_64 3
		.amdhsa_dx10_clamp 1
		.amdhsa_ieee_mode 1
		.amdhsa_fp16_overflow 0
		.amdhsa_tg_split 0
		.amdhsa_exception_fp_ieee_invalid_op 0
		.amdhsa_exception_fp_denorm_src 0
		.amdhsa_exception_fp_ieee_div_zero 0
		.amdhsa_exception_fp_ieee_overflow 0
		.amdhsa_exception_fp_ieee_underflow 0
		.amdhsa_exception_fp_ieee_inexact 0
		.amdhsa_exception_int_div_zero 0
	.end_amdhsa_kernel

; __global__ void __launch_bounds__(NWAVES * 64, 2) fwd(Args args) {
amdhsa.kernels:
  - .agpr_count:     0
    .args:
      - .offset:         0
        .size:           152
        .value_kind:     by_value
      - .offset:         152
        .size:           4
        .value_kind:     hidden_block_count_x
      - .offset:         156
        .size:           4
        .value_kind:     hidden_block_count_y
      - .offset:         160
        .size:           4
        .value_kind:     hidden_block_count_z
      - .offset:         164
        .size:           2
        .value_kind:     hidden_group_size_x
      - .offset:         166
        .size:           2
        .value_kind:     hidden_group_size_y
      - .offset:         168
        .size:           2
        .value_kind:     hidden_group_size_z
      - .offset:         170
        .size:           2
        .value_kind:     hidden_remainder_x
      - .offset:         172
        .size:           2
        .value_kind:     hidden_remainder_y
      - .offset:         174
        .size:           2
        .value_kind:     hidden_remainder_z
      - .offset:         192
        .size:           8
        .value_kind:     hidden_global_offset_x
      - .offset:         200
        .size:           8
        .value_kind:     hidden_global_offset_y
      - .offset:         208
        .size:           8
        .value_kind:     hidden_global_offset_z
      - .offset:         216
        .size:           2
        .value_kind:     hidden_grid_dims
      - .offset:         272
        .size:           4
        .value_kind:     hidden_dynamic_lds_size
    .group_segment_fixed_size: 0
    .kernarg_segment_align: 8
    .kernarg_segment_size: 408
    .language:       OpenCL C
    .language_version:
      - 2
      - 0
    .max_flat_workgroup_size: 512
    .name:           _Z3fwd4Args
    .private_segment_fixed_size: 0
    .sgpr_count:     108
    .sgpr_spill_count: 22
    .symbol:         _Z3fwd4Args.kd
    .uniform_work_group_size: 1
    .uses_dynamic_stack: false
    .vgpr_count:     256
    .vgpr_spill_count: 0
    .wavefront_size: 64
